# out-proj / down-proj epilogues: row sum of squares crosses the 16-lane rows via v_permlane16_swap / v_permlane32_swap instead of ds_bpermute
# baseline (speedup 1.0000x reference)
.Lal862m:
	s_waitcnt vmcnt(0)
	v_and_b32_e32 v243, 0xffff0000, v188
	v_cndmask_b32_e32 v242, v239, v242, vcc
	v_lshlrev_b32_e32 v252, 2, v242
	v_lshlrev_b32_e32 v242, 16, v188
	v_lshlrev_b32_e32 v188, 16, v189
	v_and_b32_e32 v189, 0xffff0000, v189
	v_pk_add_f32 v[152:153], v[152:153], v[242:243]
	v_pk_add_f32 v[154:155], v[154:155], v[188:189]
	v_cvt_pk_bf16_f32 v152, v152, v153
	v_cvt_pk_bf16_f32 v153, v154, v155
	v_lshlrev_b32_e32 v154, 16, v190
	v_and_b32_e32 v155, 0xffff0000, v190
	v_pk_add_f32 v[144:145], v[144:145], v[154:155]
	s_nop 0
	v_cvt_pk_bf16_f32 v154, v144, v145
	v_lshlrev_b32_e32 v144, 16, v191
	v_and_b32_e32 v145, 0xffff0000, v191
	v_pk_add_f32 v[144:145], v[146:147], v[144:145]
	v_and_b32_e32 v147, 0xffff0000, v152
	v_cvt_pk_bf16_f32 v155, v144, v145
	v_lshl_add_u64 v[144:145], s[12:13], 0, v[234:235]
	v_lshl_add_u64 v[144:145], v[144:145], 0, v[232:233]
	global_store_dwordx4 v[144:145], v[152:155], off
	v_lshlrev_b32_e32 v146, 16, v152
	v_mul_f32_e32 v147, v147, v147
	v_lshlrev_b32_e32 v152, 16, v153
	v_and_b32_e32 v153, 0xffff0000, v153
	v_fmac_f32_e32 v147, v146, v146
	v_mul_f32_e32 v146, v153, v153
	v_lshlrev_b32_e32 v188, 16, v154
	v_and_b32_e32 v154, 0xffff0000, v154
	v_lshlrev_b32_e32 v189, 16, v155
	v_and_b32_e32 v155, 0xffff0000, v155
	v_fmac_f32_e32 v146, v152, v152
	v_add_f32_e32 v146, v147, v146
	v_mul_f32_e32 v147, v154, v154
	v_mul_f32_e32 v152, v155, v155
	v_fmac_f32_e32 v147, v188, v188
	v_fmac_f32_e32 v152, v189, v189
	v_add_f32_e32 v147, v147, v152
	v_add_f32_e32 v152, v146, v147
	v_lshlrev_b32_e32 v146, 16, v184
	v_and_b32_e32 v147, 0xffff0000, v184
	v_pk_add_f32 v[132:133], v[132:133], v[146:147]
	v_lshlrev_b32_e32 v146, 16, v185
	v_and_b32_e32 v147, 0xffff0000, v185
	v_pk_add_f32 v[134:135], v[134:135], v[146:147]
	v_cvt_pk_bf16_f32 v132, v132, v133
	v_cvt_pk_bf16_f32 v133, v134, v135
	v_lshlrev_b32_e32 v134, 16, v186
	v_and_b32_e32 v135, 0xffff0000, v186
	v_pk_add_f32 v[128:129], v[128:129], v[134:135]
	s_nop 0
	v_cvt_pk_bf16_f32 v134, v128, v129
	v_lshlrev_b32_e32 v128, 16, v187
	v_and_b32_e32 v129, 0xffff0000, v187
	v_pk_add_f32 v[128:129], v[130:131], v[128:129]
	v_and_b32_e32 v131, 0xffff0000, v133
	v_cvt_pk_bf16_f32 v135, v128, v129
	v_and_b32_e32 v129, 0xffff0000, v132
	v_lshlrev_b32_e32 v128, 16, v132
	v_mul_f32_e32 v129, v129, v129
	v_lshlrev_b32_e32 v130, 16, v133
	v_fmac_f32_e32 v129, v128, v128
	v_mul_f32_e32 v128, v131, v131
	global_store_dwordx4 v[144:145], v[132:135], off offset:256
	v_fmac_f32_e32 v128, v130, v130
	v_add_f32_e32 v128, v129, v128
	v_lshlrev_b32_e32 v132, 16, v134
	v_and_b32_e32 v133, 0xffff0000, v134
	v_lshlrev_b32_e32 v134, 16, v135
	v_and_b32_e32 v135, 0xffff0000, v135
	v_mul_f32_e32 v129, v133, v133
	v_mul_f32_e32 v130, v135, v135
	v_fmac_f32_e32 v129, v132, v132
	v_fmac_f32_e32 v130, v134, v134
	v_add_f32_e32 v129, v129, v130
	v_add_f32_e32 v128, v128, v129
	v_add_f32_e32 v128, v152, v128
	v_mov_b32_e32 v129, v128
	s_nop 1
	v_permlane16_swap_b32 v129, v128
	s_waitcnt lgkmcnt(0)
	v_add_f32_e32 v128, v128, v129
	v_mov_b32_e32 v129, v128
	s_nop 1
	v_permlane32_swap_b32 v129, v128
	s_and_saveexec_b64 s[30:31], s[6:7]
	s_movk_i32 s82, 0x180
	s_cbranch_execz .LBB0_864
	s_waitcnt lgkmcnt(0)
	v_add_f32_e32 v130, v128, v129
	v_lshlrev_b64 v[128:129], 6, v[214:215]
	v_lshl_add_u64 v[128:129], s[14:15], 0, v[128:129]
	v_lshl_add_u64 v[128:129], s[28:29], 2, v[128:129]
	s_lshl_b32 s68, s51, 2
	v_lshl_add_u64 v[128:129], v[128:129], 0, s[68:69]
	global_store_dword v[128:129], v130, off
.LBB0_864:
	s_or_b64 exec, exec, s[30:31]
	v_lshlrev_b32_e32 v128, 16, v180
	s_waitcnt lgkmcnt(0)
	v_and_b32_e32 v129, 0xffff0000, v180
	v_pk_add_f32 v[120:121], v[120:121], v[128:129]
	v_lshlrev_b32_e32 v128, 16, v181
	v_and_b32_e32 v129, 0xffff0000, v181
	v_pk_add_f32 v[122:123], v[122:123], v[128:129]
	v_cvt_pk_bf16_f32 v120, v120, v121
	v_cvt_pk_bf16_f32 v121, v122, v123
	v_lshlrev_b32_e32 v122, 16, v182
	v_and_b32_e32 v123, 0xffff0000, v182
	v_pk_add_f32 v[116:117], v[116:117], v[122:123]
	s_nop 0
	v_cvt_pk_bf16_f32 v122, v116, v117
	v_lshlrev_b32_e32 v116, 16, v183
	v_and_b32_e32 v117, 0xffff0000, v183
	v_pk_add_f32 v[116:117], v[118:119], v[116:117]
	v_and_b32_e32 v119, 0xffff0000, v121
	v_cvt_pk_bf16_f32 v123, v116, v117
	v_and_b32_e32 v117, 0xffff0000, v120
	v_lshlrev_b32_e32 v116, 16, v120
	v_mul_f32_e32 v117, v117, v117
	v_lshlrev_b32_e32 v118, 16, v121
	v_fmac_f32_e32 v117, v116, v116
	v_mul_f32_e32 v116, v119, v119
	v_and_b32_e32 v129, 0xffff0000, v122
	v_and_b32_e32 v131, 0xffff0000, v123
	v_fmac_f32_e32 v116, v118, v118
	v_lshlrev_b32_e32 v128, 16, v122
	v_lshlrev_b32_e32 v130, 16, v123
	v_add_f32_e32 v116, v117, v116
	v_mul_f32_e32 v117, v129, v129
	v_mul_f32_e32 v118, v131, v131
	v_fmac_f32_e32 v117, v128, v128
	v_fmac_f32_e32 v118, v130, v130
	v_add_f32_e32 v117, v117, v118
	v_add_f32_e32 v118, v116, v117
	v_lshlrev_b32_e32 v116, 16, v176
	v_and_b32_e32 v117, 0xffff0000, v176
	v_pk_add_f32 v[108:109], v[108:109], v[116:117]
	v_lshlrev_b32_e32 v116, 16, v177
	v_and_b32_e32 v117, 0xffff0000, v177
	v_pk_add_f32 v[110:111], v[110:111], v[116:117]
	v_cvt_pk_bf16_f32 v108, v108, v109
	v_cvt_pk_bf16_f32 v109, v110, v111
	v_lshlrev_b32_e32 v110, 16, v178
	v_and_b32_e32 v111, 0xffff0000, v178
	v_pk_add_f32 v[104:105], v[104:105], v[110:111]
	s_nop 0
	v_cvt_pk_bf16_f32 v110, v104, v105
	v_lshlrev_b32_e32 v104, 16, v179
	v_and_b32_e32 v105, 0xffff0000, v179
	v_pk_add_f32 v[104:105], v[106:107], v[104:105]
	v_and_b32_e32 v107, 0xffff0000, v109
	v_cvt_pk_bf16_f32 v111, v104, v105
	v_and_b32_e32 v105, 0xffff0000, v108
	v_lshlrev_b32_e32 v104, 16, v108
	v_mul_f32_e32 v105, v105, v105
	v_lshlrev_b32_e32 v106, 16, v109
	v_fmac_f32_e32 v105, v104, v104
	v_mul_f32_e32 v104, v107, v107
	v_and_b32_e32 v117, 0xffff0000, v110
	v_and_b32_e32 v128, 0xffff0000, v111
	v_fmac_f32_e32 v104, v106, v106
	v_lshlrev_b32_e32 v116, 16, v110
	v_lshlrev_b32_e32 v119, 16, v111
	v_add_f32_e32 v104, v105, v104
	v_mul_f32_e32 v105, v117, v117
	v_mul_f32_e32 v106, v128, v128
	v_fmac_f32_e32 v105, v116, v116
	v_fmac_f32_e32 v106, v119, v119
	v_add_f32_e32 v105, v105, v106
	v_add_f32_e32 v104, v104, v105
	v_add_f32_e32 v104, v118, v104
	v_mov_b32_e32 v105, v104
	s_nop 1
	v_permlane16_swap_b32 v105, v104
	v_lshl_add_u64 v[106:107], s[12:13], 0, v[230:231]
	v_lshl_add_u64 v[106:107], v[212:213], 1, v[106:107]
	global_store_dwordx4 v[106:107], v[120:123], off
	global_store_dwordx4 v[106:107], v[108:111], off offset:256
	s_waitcnt lgkmcnt(0)
	v_add_f32_e32 v104, v104, v105
	v_mov_b32_e32 v105, v104
	s_nop 1
	v_permlane32_swap_b32 v105, v104
	s_and_saveexec_b64 s[30:31], s[6:7]
	s_cbranch_execz .LBB0_866
	s_waitcnt lgkmcnt(0)
	v_add_f32_e32 v106, v104, v105
	v_lshlrev_b64 v[104:105], 6, v[228:229]
	v_lshl_add_u64 v[104:105], s[14:15], 0, v[104:105]
	v_lshl_add_u64 v[104:105], s[28:29], 2, v[104:105]
	s_lshl_b32 s68, s51, 2
	v_lshl_add_u64 v[104:105], v[104:105], 0, s[68:69]
	global_store_dword v[104:105], v106, off
.LBB0_866:
	s_or_b64 exec, exec, s[30:31]
	v_lshlrev_b32_e32 v104, 16, v172
	s_waitcnt lgkmcnt(0)
	v_and_b32_e32 v105, 0xffff0000, v172
	v_pk_add_f32 v[96:97], v[96:97], v[104:105]
	v_lshlrev_b32_e32 v104, 16, v173
	v_and_b32_e32 v105, 0xffff0000, v173
	v_pk_add_f32 v[98:99], v[98:99], v[104:105]
	v_cvt_pk_bf16_f32 v96, v96, v97
	v_cvt_pk_bf16_f32 v97, v98, v99
	v_lshlrev_b32_e32 v98, 16, v174
	v_and_b32_e32 v99, 0xffff0000, v174
	v_pk_add_f32 v[92:93], v[92:93], v[98:99]
	s_nop 0
	v_cvt_pk_bf16_f32 v98, v92, v93
	v_lshlrev_b32_e32 v92, 16, v175
	v_and_b32_e32 v93, 0xffff0000, v175
	v_pk_add_f32 v[92:93], v[94:95], v[92:93]
	v_and_b32_e32 v95, 0xffff0000, v97
	v_cvt_pk_bf16_f32 v99, v92, v93
	v_and_b32_e32 v93, 0xffff0000, v96
	v_lshlrev_b32_e32 v92, 16, v96
	v_mul_f32_e32 v93, v93, v93
	v_lshlrev_b32_e32 v94, 16, v97
	v_fmac_f32_e32 v93, v92, v92
	v_mul_f32_e32 v92, v95, v95
	v_and_b32_e32 v105, 0xffff0000, v98
	v_and_b32_e32 v107, 0xffff0000, v99
	v_fmac_f32_e32 v92, v94, v94
	v_lshlrev_b32_e32 v104, 16, v98
	v_lshlrev_b32_e32 v106, 16, v99
	v_add_f32_e32 v92, v93, v92
	v_mul_f32_e32 v93, v105, v105
	v_mul_f32_e32 v94, v107, v107
	v_fmac_f32_e32 v93, v104, v104
	v_fmac_f32_e32 v94, v106, v106
	v_add_f32_e32 v93, v93, v94
	v_add_f32_e32 v94, v92, v93
	v_lshlrev_b32_e32 v92, 16, v168
	v_and_b32_e32 v93, 0xffff0000, v168
	v_pk_add_f32 v[84:85], v[84:85], v[92:93]
	v_lshlrev_b32_e32 v92, 16, v169
	v_and_b32_e32 v93, 0xffff0000, v169
	v_pk_add_f32 v[86:87], v[86:87], v[92:93]
	v_cvt_pk_bf16_f32 v84, v84, v85
	v_cvt_pk_bf16_f32 v85, v86, v87
	v_lshlrev_b32_e32 v86, 16, v170
	v_and_b32_e32 v87, 0xffff0000, v170
	v_pk_add_f32 v[80:81], v[80:81], v[86:87]
	s_nop 0
	v_cvt_pk_bf16_f32 v86, v80, v81
	v_lshlrev_b32_e32 v80, 16, v171
	v_and_b32_e32 v81, 0xffff0000, v171
	v_pk_add_f32 v[80:81], v[82:83], v[80:81]
	v_and_b32_e32 v83, 0xffff0000, v85
	v_cvt_pk_bf16_f32 v87, v80, v81
	v_and_b32_e32 v81, 0xffff0000, v84
	v_lshlrev_b32_e32 v80, 16, v84
	v_mul_f32_e32 v81, v81, v81
	v_lshlrev_b32_e32 v82, 16, v85
	v_fmac_f32_e32 v81, v80, v80
	v_mul_f32_e32 v80, v83, v83
	v_and_b32_e32 v93, 0xffff0000, v86
	v_and_b32_e32 v104, 0xffff0000, v87
	v_fmac_f32_e32 v80, v82, v82
	v_lshlrev_b32_e32 v92, 16, v86
	v_lshlrev_b32_e32 v95, 16, v87
	v_add_f32_e32 v80, v81, v80
	v_mul_f32_e32 v81, v93, v93
	v_mul_f32_e32 v82, v104, v104
	v_fmac_f32_e32 v81, v92, v92
	v_fmac_f32_e32 v82, v95, v95
	v_add_f32_e32 v81, v81, v82
	v_add_f32_e32 v80, v80, v81
	v_add_f32_e32 v80, v94, v80
	v_mov_b32_e32 v81, v80
	s_nop 1
	v_permlane16_swap_b32 v81, v80
	v_lshl_add_u64 v[82:83], s[12:13], 0, v[226:227]
	v_lshl_add_u64 v[82:83], v[212:213], 1, v[82:83]
	global_store_dwordx4 v[82:83], v[96:99], off
	global_store_dwordx4 v[82:83], v[84:87], off offset:256
	s_waitcnt lgkmcnt(0)
	v_add_f32_e32 v80, v80, v81
	v_mov_b32_e32 v81, v80
	s_nop 1
	v_permlane32_swap_b32 v81, v80
	s_and_saveexec_b64 s[30:31], s[6:7]
	s_cbranch_execz .LBB0_868
	s_waitcnt lgkmcnt(0)
	v_add_f32_e32 v82, v80, v81
	v_lshlrev_b64 v[80:81], 6, v[224:225]
	v_lshl_add_u64 v[80:81], s[14:15], 0, v[80:81]
	v_lshl_add_u64 v[80:81], s[28:29], 2, v[80:81]
	s_lshl_b32 s68, s51, 2
	v_lshl_add_u64 v[80:81], v[80:81], 0, s[68:69]
	global_store_dword v[80:81], v82, off
.LBB0_868:
	s_or_b64 exec, exec, s[30:31]
	v_lshlrev_b32_e32 v80, 16, v164
	s_waitcnt lgkmcnt(0)
	v_and_b32_e32 v81, 0xffff0000, v164
	v_pk_add_f32 v[76:77], v[76:77], v[80:81]
	v_lshlrev_b32_e32 v80, 16, v165
	v_and_b32_e32 v81, 0xffff0000, v165
	v_pk_add_f32 v[78:79], v[78:79], v[80:81]
	v_cvt_pk_bf16_f32 v76, v76, v77
	v_cvt_pk_bf16_f32 v77, v78, v79
	v_lshlrev_b32_e32 v78, 16, v166
	v_and_b32_e32 v79, 0xffff0000, v166
	v_pk_add_f32 v[72:73], v[72:73], v[78:79]
	s_nop 0
	v_cvt_pk_bf16_f32 v78, v72, v73
	v_lshlrev_b32_e32 v72, 16, v167
	v_and_b32_e32 v73, 0xffff0000, v167
	v_pk_add_f32 v[72:73], v[74:75], v[72:73]
	v_and_b32_e32 v75, 0xffff0000, v77
	v_cvt_pk_bf16_f32 v79, v72, v73
	v_and_b32_e32 v73, 0xffff0000, v76
	v_lshlrev_b32_e32 v72, 16, v76
	v_mul_f32_e32 v73, v73, v73
	v_lshlrev_b32_e32 v74, 16, v77
	v_fmac_f32_e32 v73, v72, v72
	v_mul_f32_e32 v72, v75, v75
	v_and_b32_e32 v81, 0xffff0000, v78
	v_and_b32_e32 v83, 0xffff0000, v79
	v_fmac_f32_e32 v72, v74, v74
	v_lshlrev_b32_e32 v80, 16, v78
	v_lshlrev_b32_e32 v82, 16, v79
	v_add_f32_e32 v72, v73, v72
	v_mul_f32_e32 v73, v81, v81
	v_mul_f32_e32 v74, v83, v83
	v_fmac_f32_e32 v73, v80, v80
	v_fmac_f32_e32 v74, v82, v82
	v_add_f32_e32 v73, v73, v74
	v_add_f32_e32 v74, v72, v73
	v_lshlrev_b32_e32 v72, 16, v160
	v_and_b32_e32 v73, 0xffff0000, v160
	v_pk_add_f32 v[68:69], v[68:69], v[72:73]
	v_lshlrev_b32_e32 v72, 16, v161
	v_and_b32_e32 v73, 0xffff0000, v161
	v_pk_add_f32 v[70:71], v[70:71], v[72:73]
	v_cvt_pk_bf16_f32 v68, v68, v69
	v_cvt_pk_bf16_f32 v69, v70, v71
	v_lshlrev_b32_e32 v70, 16, v162
	v_and_b32_e32 v71, 0xffff0000, v162
	v_pk_add_f32 v[64:65], v[64:65], v[70:71]
	s_nop 0
	v_cvt_pk_bf16_f32 v70, v64, v65
	v_lshlrev_b32_e32 v64, 16, v163
	v_and_b32_e32 v65, 0xffff0000, v163
	v_pk_add_f32 v[64:65], v[66:67], v[64:65]
	v_and_b32_e32 v67, 0xffff0000, v69
	v_cvt_pk_bf16_f32 v71, v64, v65
	v_and_b32_e32 v65, 0xffff0000, v68
	v_lshlrev_b32_e32 v64, 16, v68
	v_mul_f32_e32 v65, v65, v65
	v_lshlrev_b32_e32 v66, 16, v69
	v_fmac_f32_e32 v65, v64, v64
	v_mul_f32_e32 v64, v67, v67
	v_and_b32_e32 v73, 0xffff0000, v70
	v_and_b32_e32 v80, 0xffff0000, v71
	v_fmac_f32_e32 v64, v66, v66
	v_lshlrev_b32_e32 v72, 16, v70
	v_lshlrev_b32_e32 v75, 16, v71
	v_add_f32_e32 v64, v65, v64
	v_mul_f32_e32 v65, v73, v73
	v_mul_f32_e32 v66, v80, v80
	v_fmac_f32_e32 v65, v72, v72
	v_fmac_f32_e32 v66, v75, v75
	v_add_f32_e32 v65, v65, v66
	v_add_f32_e32 v64, v64, v65
	v_add_f32_e32 v64, v74, v64
	v_mov_b32_e32 v65, v64
	s_nop 1
	v_permlane16_swap_b32 v65, v64
	v_lshl_add_u64 v[66:67], s[12:13], 0, v[222:223]
	v_lshl_add_u64 v[66:67], v[212:213], 1, v[66:67]
	global_store_dwordx4 v[66:67], v[76:79], off
	global_store_dwordx4 v[66:67], v[68:71], off offset:256
	s_waitcnt lgkmcnt(0)
	v_add_f32_e32 v64, v64, v65
	v_mov_b32_e32 v65, v64
	s_nop 1
	v_permlane32_swap_b32 v65, v64
	s_and_saveexec_b64 s[30:31], s[6:7]
	s_cbranch_execz .LBB0_870
	s_waitcnt lgkmcnt(0)
	v_add_f32_e32 v66, v64, v65
	v_lshlrev_b64 v[64:65], 6, v[220:221]
	v_lshl_add_u64 v[64:65], s[14:15], 0, v[64:65]
	v_lshl_add_u64 v[64:65], s[28:29], 2, v[64:65]
	s_lshl_b32 s68, s51, 2
	v_lshl_add_u64 v[64:65], v[64:65], 0, s[68:69]
	global_store_dword v[64:65], v66, off
.LBB0_870:
	s_or_b64 exec, exec, s[30:31]
	v_lshlrev_b32_e32 v64, 16, v156
	s_waitcnt lgkmcnt(0)
	v_and_b32_e32 v65, 0xffff0000, v156
	v_pk_add_f32 v[60:61], v[60:61], v[64:65]
	v_lshlrev_b32_e32 v64, 16, v157
	v_and_b32_e32 v65, 0xffff0000, v157
	v_pk_add_f32 v[62:63], v[62:63], v[64:65]
	v_cvt_pk_bf16_f32 v60, v60, v61
	v_cvt_pk_bf16_f32 v61, v62, v63
	v_lshlrev_b32_e32 v62, 16, v158
	v_and_b32_e32 v63, 0xffff0000, v158
	v_pk_add_f32 v[56:57], v[56:57], v[62:63]
	s_nop 0
	v_cvt_pk_bf16_f32 v62, v56, v57
	v_lshlrev_b32_e32 v56, 16, v159
	v_and_b32_e32 v57, 0xffff0000, v159
	v_pk_add_f32 v[56:57], v[58:59], v[56:57]
	v_and_b32_e32 v59, 0xffff0000, v61
	v_cvt_pk_bf16_f32 v63, v56, v57
	v_and_b32_e32 v57, 0xffff0000, v60
	v_lshlrev_b32_e32 v56, 16, v60
	v_mul_f32_e32 v57, v57, v57
	v_lshlrev_b32_e32 v58, 16, v61
	v_fmac_f32_e32 v57, v56, v56
	v_mul_f32_e32 v56, v59, v59
	v_and_b32_e32 v65, 0xffff0000, v62
	v_and_b32_e32 v67, 0xffff0000, v63
	v_fmac_f32_e32 v56, v58, v58
	v_lshlrev_b32_e32 v64, 16, v62
	v_lshlrev_b32_e32 v66, 16, v63
	v_add_f32_e32 v56, v57, v56
	v_mul_f32_e32 v57, v65, v65
	v_mul_f32_e32 v58, v67, v67
	v_fmac_f32_e32 v57, v64, v64
	v_fmac_f32_e32 v58, v66, v66
	v_add_f32_e32 v57, v57, v58
	v_add_f32_e32 v58, v56, v57
	v_lshlrev_b32_e32 v56, 16, v148
	v_and_b32_e32 v57, 0xffff0000, v148
	v_pk_add_f32 v[52:53], v[52:53], v[56:57]
	v_lshlrev_b32_e32 v56, 16, v149
	v_and_b32_e32 v57, 0xffff0000, v149
	v_pk_add_f32 v[54:55], v[54:55], v[56:57]
	v_cvt_pk_bf16_f32 v52, v52, v53
	v_cvt_pk_bf16_f32 v53, v54, v55
	v_lshlrev_b32_e32 v54, 16, v150
	v_and_b32_e32 v55, 0xffff0000, v150
	v_pk_add_f32 v[48:49], v[48:49], v[54:55]
	s_nop 0
	v_cvt_pk_bf16_f32 v54, v48, v49
	v_lshlrev_b32_e32 v48, 16, v151
	v_and_b32_e32 v49, 0xffff0000, v151
	v_pk_add_f32 v[48:49], v[50:51], v[48:49]
	v_and_b32_e32 v51, 0xffff0000, v53
	v_cvt_pk_bf16_f32 v55, v48, v49
	v_and_b32_e32 v49, 0xffff0000, v52
	v_lshlrev_b32_e32 v48, 16, v52
	v_mul_f32_e32 v49, v49, v49
	v_lshlrev_b32_e32 v50, 16, v53
	v_fmac_f32_e32 v49, v48, v48
	v_mul_f32_e32 v48, v51, v51
	v_and_b32_e32 v57, 0xffff0000, v54
	v_and_b32_e32 v64, 0xffff0000, v55
	v_fmac_f32_e32 v48, v50, v50
	v_lshlrev_b32_e32 v56, 16, v54
	v_lshlrev_b32_e32 v59, 16, v55
	v_add_f32_e32 v48, v49, v48
	v_mul_f32_e32 v49, v57, v57
	v_mul_f32_e32 v50, v64, v64
	v_fmac_f32_e32 v49, v56, v56
	v_fmac_f32_e32 v50, v59, v59
	v_add_f32_e32 v49, v49, v50
	v_add_f32_e32 v48, v48, v49
	v_add_f32_e32 v48, v58, v48
	v_mov_b32_e32 v49, v48
	s_nop 1
	v_permlane16_swap_b32 v49, v48
	v_lshl_add_u64 v[50:51], s[12:13], 0, v[218:219]
	v_lshl_add_u64 v[50:51], v[212:213], 1, v[50:51]
	global_store_dwordx4 v[50:51], v[60:63], off
	global_store_dwordx4 v[50:51], v[52:55], off offset:256
	s_waitcnt lgkmcnt(0)
	v_add_f32_e32 v48, v48, v49
	v_mov_b32_e32 v49, v48
	s_nop 1
	v_permlane32_swap_b32 v49, v48
	s_and_saveexec_b64 s[30:31], s[6:7]
	s_cbranch_execz .LBB0_872
	s_waitcnt lgkmcnt(0)
	v_add_f32_e32 v50, v48, v49
	v_lshlrev_b64 v[48:49], 6, v[216:217]
	v_lshl_add_u64 v[48:49], s[14:15], 0, v[48:49]
	v_lshl_add_u64 v[48:49], s[28:29], 2, v[48:49]
	s_lshl_b32 s68, s51, 2
	v_lshl_add_u64 v[48:49], v[48:49], 0, s[68:69]
	global_store_dword v[48:49], v50, off
.LBB0_872:
	s_or_b64 exec, exec, s[30:31]
	v_lshlrev_b32_e32 v48, 16, v140
	s_waitcnt lgkmcnt(0)
	v_and_b32_e32 v49, 0xffff0000, v140
	v_pk_add_f32 v[44:45], v[44:45], v[48:49]
	v_lshlrev_b32_e32 v48, 16, v141
	v_and_b32_e32 v49, 0xffff0000, v141
	v_pk_add_f32 v[46:47], v[46:47], v[48:49]
	v_cvt_pk_bf16_f32 v44, v44, v45
	v_cvt_pk_bf16_f32 v45, v46, v47
	v_lshlrev_b32_e32 v46, 16, v142
	v_and_b32_e32 v47, 0xffff0000, v142
	v_pk_add_f32 v[40:41], v[40:41], v[46:47]
	s_nop 0
	v_cvt_pk_bf16_f32 v46, v40, v41
	v_lshlrev_b32_e32 v40, 16, v143
	v_and_b32_e32 v41, 0xffff0000, v143
	v_pk_add_f32 v[40:41], v[42:43], v[40:41]
	v_and_b32_e32 v43, 0xffff0000, v45
	v_cvt_pk_bf16_f32 v47, v40, v41
	v_and_b32_e32 v41, 0xffff0000, v44
	v_lshlrev_b32_e32 v40, 16, v44
	v_mul_f32_e32 v41, v41, v41
	v_lshlrev_b32_e32 v42, 16, v45
	v_fmac_f32_e32 v41, v40, v40
	v_mul_f32_e32 v40, v43, v43
	v_and_b32_e32 v49, 0xffff0000, v46
	v_and_b32_e32 v51, 0xffff0000, v47
	v_fmac_f32_e32 v40, v42, v42
	v_lshlrev_b32_e32 v48, 16, v46
	v_lshlrev_b32_e32 v50, 16, v47
	v_add_f32_e32 v40, v41, v40
	v_mul_f32_e32 v41, v49, v49
	v_mul_f32_e32 v42, v51, v51
	v_fmac_f32_e32 v41, v48, v48
	v_fmac_f32_e32 v42, v50, v50
	v_add_f32_e32 v41, v41, v42
	v_add_f32_e32 v42, v40, v41
	v_lshlrev_b32_e32 v40, 16, v136
	v_and_b32_e32 v41, 0xffff0000, v136
	v_pk_add_f32 v[36:37], v[36:37], v[40:41]
	v_lshlrev_b32_e32 v40, 16, v137
	v_and_b32_e32 v41, 0xffff0000, v137
	v_pk_add_f32 v[38:39], v[38:39], v[40:41]
	v_cvt_pk_bf16_f32 v36, v36, v37
	v_cvt_pk_bf16_f32 v37, v38, v39
	v_lshlrev_b32_e32 v38, 16, v138
	v_and_b32_e32 v39, 0xffff0000, v138
	v_pk_add_f32 v[32:33], v[32:33], v[38:39]
	s_nop 0
	v_cvt_pk_bf16_f32 v38, v32, v33
	v_lshlrev_b32_e32 v32, 16, v139
	v_and_b32_e32 v33, 0xffff0000, v139
	v_pk_add_f32 v[32:33], v[34:35], v[32:33]
	v_and_b32_e32 v35, 0xffff0000, v37
	v_cvt_pk_bf16_f32 v39, v32, v33
	v_and_b32_e32 v33, 0xffff0000, v36
	v_lshlrev_b32_e32 v32, 16, v36
	v_mul_f32_e32 v33, v33, v33
	v_lshlrev_b32_e32 v34, 16, v37
	v_fmac_f32_e32 v33, v32, v32
	v_mul_f32_e32 v32, v35, v35
	v_and_b32_e32 v41, 0xffff0000, v38
	v_and_b32_e32 v48, 0xffff0000, v39
	v_fmac_f32_e32 v32, v34, v34
	v_lshlrev_b32_e32 v40, 16, v38
	v_lshlrev_b32_e32 v43, 16, v39
	v_add_f32_e32 v32, v33, v32
	v_mul_f32_e32 v33, v41, v41
	v_mul_f32_e32 v34, v48, v48
	v_fmac_f32_e32 v33, v40, v40
	v_fmac_f32_e32 v34, v43, v43
	v_add_f32_e32 v33, v33, v34
	v_add_f32_e32 v32, v32, v33
	v_add_f32_e32 v34, v42, v32
	v_mov_b32_e32 v35, v34
	s_nop 1
	v_permlane16_swap_b32 v35, v34
	v_add_u32_e32 v32, 0x90, v214
	v_ashrrev_i32_e32 v33, 31, v32
	v_lshlrev_b64 v[40:41], 11, v[32:33]
	v_lshl_add_u64 v[40:41], s[12:13], 0, v[40:41]
	s_waitcnt lgkmcnt(0)
	v_add_f32_e32 v34, v34, v35
	v_mov_b32_e32 v35, v34
	s_nop 1
	v_permlane32_swap_b32 v35, v34
	v_lshl_add_u64 v[40:41], v[212:213], 1, v[40:41]
	global_store_dwordx4 v[40:41], v[44:47], off
	global_store_dwordx4 v[40:41], v[36:39], off offset:256
	s_and_saveexec_b64 s[30:31], s[6:7]
	s_cbranch_execz .LBB0_874
	v_lshlrev_b64 v[32:33], 6, v[32:33]
	v_lshl_add_u64 v[32:33], s[14:15], 0, v[32:33]
	v_lshl_add_u64 v[32:33], s[28:29], 2, v[32:33]
	s_lshl_b32 s68, s51, 2
	s_waitcnt lgkmcnt(0)
	v_add_f32_e32 v34, v34, v35
	v_lshl_add_u64 v[32:33], v[32:33], 0, s[68:69]
	global_store_dword v[32:33], v34, off
.LBB0_874:
	s_or_b64 exec, exec, s[30:31]
	v_lshlrev_b32_e32 v32, 16, v124
	v_and_b32_e32 v33, 0xffff0000, v124
	v_pk_add_f32 v[28:29], v[28:29], v[32:33]
	v_lshlrev_b32_e32 v32, 16, v125
	v_and_b32_e32 v33, 0xffff0000, v125
	v_pk_add_f32 v[30:31], v[30:31], v[32:33]
	v_cvt_pk_bf16_f32 v28, v28, v29
	v_cvt_pk_bf16_f32 v29, v30, v31
	v_lshlrev_b32_e32 v30, 16, v126
	v_and_b32_e32 v31, 0xffff0000, v126
	v_pk_add_f32 v[24:25], v[24:25], v[30:31]
	s_nop 0
	v_cvt_pk_bf16_f32 v30, v24, v25
	v_lshlrev_b32_e32 v24, 16, v127
	v_and_b32_e32 v25, 0xffff0000, v127
	v_pk_add_f32 v[24:25], v[26:27], v[24:25]
	v_and_b32_e32 v27, 0xffff0000, v29
	v_cvt_pk_bf16_f32 v31, v24, v25
	v_and_b32_e32 v25, 0xffff0000, v28
	v_lshlrev_b32_e32 v24, 16, v28
	v_mul_f32_e32 v25, v25, v25
	v_lshlrev_b32_e32 v26, 16, v29
	v_fmac_f32_e32 v25, v24, v24
	v_mul_f32_e32 v24, v27, v27
	v_and_b32_e32 v33, 0xffff0000, v30
	s_waitcnt lgkmcnt(0)
	v_and_b32_e32 v35, 0xffff0000, v31
	v_fmac_f32_e32 v24, v26, v26
	v_lshlrev_b32_e32 v32, 16, v30
	v_lshlrev_b32_e32 v34, 16, v31
	v_add_f32_e32 v24, v25, v24
	v_mul_f32_e32 v25, v33, v33
	v_mul_f32_e32 v26, v35, v35
	v_fmac_f32_e32 v25, v32, v32
	v_fmac_f32_e32 v26, v34, v34
	v_add_f32_e32 v25, v25, v26
	v_add_f32_e32 v26, v24, v25
	v_lshlrev_b32_e32 v24, 16, v112
	v_and_b32_e32 v25, 0xffff0000, v112
	v_pk_add_f32 v[20:21], v[20:21], v[24:25]
	v_lshlrev_b32_e32 v24, 16, v113
	v_and_b32_e32 v25, 0xffff0000, v113
	v_pk_add_f32 v[22:23], v[22:23], v[24:25]
	v_cvt_pk_bf16_f32 v20, v20, v21
	v_cvt_pk_bf16_f32 v21, v22, v23
	v_lshlrev_b32_e32 v22, 16, v114
	v_and_b32_e32 v23, 0xffff0000, v114
	v_pk_add_f32 v[16:17], v[16:17], v[22:23]
	s_nop 0
	v_cvt_pk_bf16_f32 v22, v16, v17
	v_lshlrev_b32_e32 v16, 16, v115
	v_and_b32_e32 v17, 0xffff0000, v115
	v_pk_add_f32 v[16:17], v[18:19], v[16:17]
	v_and_b32_e32 v19, 0xffff0000, v21
	v_cvt_pk_bf16_f32 v23, v16, v17
	v_and_b32_e32 v17, 0xffff0000, v20
	v_lshlrev_b32_e32 v16, 16, v20
	v_mul_f32_e32 v17, v17, v17
	v_lshlrev_b32_e32 v18, 16, v21
	v_fmac_f32_e32 v17, v16, v16
	v_mul_f32_e32 v16, v19, v19
	v_and_b32_e32 v25, 0xffff0000, v22
	v_and_b32_e32 v32, 0xffff0000, v23
	v_fmac_f32_e32 v16, v18, v18
	v_lshlrev_b32_e32 v24, 16, v22
	v_lshlrev_b32_e32 v27, 16, v23
	v_add_f32_e32 v16, v17, v16
	v_mul_f32_e32 v17, v25, v25
	v_mul_f32_e32 v18, v32, v32
	v_fmac_f32_e32 v17, v24, v24
	v_fmac_f32_e32 v18, v27, v27
	v_add_f32_e32 v17, v17, v18
	v_add_f32_e32 v16, v16, v17
	v_add_f32_e32 v18, v26, v16
	v_mov_b32_e32 v19, v18
	s_nop 1
	v_permlane16_swap_b32 v19, v18
	v_add_u32_e32 v16, 0xa0, v214
	v_ashrrev_i32_e32 v17, 31, v16
	v_lshlrev_b64 v[24:25], 11, v[16:17]
	v_lshl_add_u64 v[24:25], s[12:13], 0, v[24:25]
	s_waitcnt lgkmcnt(0)
	v_add_f32_e32 v18, v18, v19
	v_mov_b32_e32 v19, v18
	s_nop 1
	v_permlane32_swap_b32 v19, v18
	v_lshl_add_u64 v[24:25], v[212:213], 1, v[24:25]
	global_store_dwordx4 v[24:25], v[28:31], off
	global_store_dwordx4 v[24:25], v[20:23], off offset:256
	s_and_saveexec_b64 s[30:31], s[6:7]
	s_cbranch_execz .LBB0_876
	v_lshlrev_b64 v[16:17], 6, v[16:17]
	v_lshl_add_u64 v[16:17], s[14:15], 0, v[16:17]
	v_lshl_add_u64 v[16:17], s[28:29], 2, v[16:17]
	s_lshl_b32 s68, s51, 2
	s_waitcnt lgkmcnt(0)
	v_add_f32_e32 v18, v18, v19
	v_lshl_add_u64 v[16:17], v[16:17], 0, s[68:69]
	global_store_dword v[16:17], v18, off
.LBB0_876:
	s_or_b64 exec, exec, s[30:31]
	v_lshlrev_b32_e32 v16, 16, v100
	v_and_b32_e32 v17, 0xffff0000, v100
	v_pk_add_f32 v[12:13], v[12:13], v[16:17]
	v_lshlrev_b32_e32 v16, 16, v101
	v_and_b32_e32 v17, 0xffff0000, v101
	v_pk_add_f32 v[14:15], v[14:15], v[16:17]
	v_cvt_pk_bf16_f32 v12, v12, v13
	v_cvt_pk_bf16_f32 v13, v14, v15
	v_lshlrev_b32_e32 v14, 16, v102
	v_and_b32_e32 v15, 0xffff0000, v102
	v_pk_add_f32 v[8:9], v[8:9], v[14:15]
	s_nop 0
	v_cvt_pk_bf16_f32 v14, v8, v9
	v_lshlrev_b32_e32 v8, 16, v103
	v_and_b32_e32 v9, 0xffff0000, v103
	v_pk_add_f32 v[8:9], v[10:11], v[8:9]
	v_and_b32_e32 v11, 0xffff0000, v13
	v_cvt_pk_bf16_f32 v15, v8, v9
	v_and_b32_e32 v9, 0xffff0000, v12
	v_lshlrev_b32_e32 v8, 16, v12
	v_mul_f32_e32 v9, v9, v9
	v_lshlrev_b32_e32 v10, 16, v13
	v_fmac_f32_e32 v9, v8, v8
	v_mul_f32_e32 v8, v11, v11
	v_and_b32_e32 v17, 0xffff0000, v14
	s_waitcnt lgkmcnt(0)
	v_and_b32_e32 v19, 0xffff0000, v15
	v_fmac_f32_e32 v8, v10, v10
	v_lshlrev_b32_e32 v16, 16, v14
	v_lshlrev_b32_e32 v18, 16, v15
	v_add_f32_e32 v8, v9, v8
	v_mul_f32_e32 v9, v17, v17
	v_mul_f32_e32 v10, v19, v19
	v_fmac_f32_e32 v9, v16, v16
	v_fmac_f32_e32 v10, v18, v18
	v_add_f32_e32 v9, v9, v10
	v_add_f32_e32 v10, v8, v9
	v_lshlrev_b32_e32 v8, 16, v88
	v_and_b32_e32 v9, 0xffff0000, v88
	v_pk_add_f32 v[4:5], v[4:5], v[8:9]
	v_lshlrev_b32_e32 v8, 16, v89
	v_and_b32_e32 v9, 0xffff0000, v89
	v_pk_add_f32 v[6:7], v[6:7], v[8:9]
	v_cvt_pk_bf16_f32 v4, v4, v5
	v_cvt_pk_bf16_f32 v5, v6, v7
	v_lshlrev_b32_e32 v6, 16, v90
	v_and_b32_e32 v7, 0xffff0000, v90
	v_pk_add_f32 v[0:1], v[0:1], v[6:7]
	s_nop 0
	v_cvt_pk_bf16_f32 v6, v0, v1
	v_lshlrev_b32_e32 v0, 16, v91
	v_and_b32_e32 v1, 0xffff0000, v91
	v_pk_add_f32 v[0:1], v[2:3], v[0:1]
	v_and_b32_e32 v3, 0xffff0000, v5
	v_cvt_pk_bf16_f32 v7, v0, v1
	v_and_b32_e32 v1, 0xffff0000, v4
	v_lshlrev_b32_e32 v0, 16, v4
	v_mul_f32_e32 v1, v1, v1
	v_lshlrev_b32_e32 v2, 16, v5
	v_fmac_f32_e32 v1, v0, v0
	v_mul_f32_e32 v0, v3, v3
	v_and_b32_e32 v9, 0xffff0000, v6
	v_and_b32_e32 v16, 0xffff0000, v7
	v_fmac_f32_e32 v0, v2, v2
	v_lshlrev_b32_e32 v8, 16, v6
	v_lshlrev_b32_e32 v11, 16, v7
	v_add_f32_e32 v0, v1, v0
	v_mul_f32_e32 v1, v9, v9
	v_mul_f32_e32 v2, v16, v16
	v_fmac_f32_e32 v1, v8, v8
	v_fmac_f32_e32 v2, v11, v11
	v_add_f32_e32 v1, v1, v2
	v_add_f32_e32 v0, v0, v1
	v_add_f32_e32 v2, v10, v0
	v_mov_b32_e32 v3, v2
	s_nop 1
	v_permlane16_swap_b32 v3, v2
	v_add_u32_e32 v0, 0xb0, v214
	v_ashrrev_i32_e32 v1, 31, v0
	v_lshlrev_b64 v[8:9], 11, v[0:1]
	v_lshl_add_u64 v[8:9], s[12:13], 0, v[8:9]
	s_waitcnt lgkmcnt(0)
	v_add_f32_e32 v2, v2, v3
	v_mov_b32_e32 v3, v2
	s_nop 1
	v_permlane32_swap_b32 v3, v2
	v_lshl_add_u64 v[8:9], v[212:213], 1, v[8:9]
	global_store_dwordx4 v[8:9], v[12:15], off
	global_store_dwordx4 v[8:9], v[4:7], off offset:256
	s_and_saveexec_b64 s[30:31], s[6:7]
	s_cbranch_execz .LBB0_878
	v_lshlrev_b64 v[0:1], 6, v[0:1]
	v_lshl_add_u64 v[0:1], s[14:15], 0, v[0:1]
	v_lshl_add_u64 v[0:1], s[28:29], 2, v[0:1]
	s_lshl_b32 s68, s51, 2
	s_waitcnt lgkmcnt(0)
	v_add_f32_e32 v2, v2, v3
	v_lshl_add_u64 v[0:1], v[0:1], 0, s[68:69]
	global_store_dword v[0:1], v2, off

.Lal1007m:
	s_waitcnt vmcnt(0)
	v_and_b32_e32 v243, 0xffff0000, v188
	v_cndmask_b32_e32 v242, v239, v242, vcc
	v_lshlrev_b32_e32 v252, 2, v242
	v_lshlrev_b32_e32 v242, 16, v188
	v_lshlrev_b32_e32 v188, 16, v189
	v_and_b32_e32 v189, 0xffff0000, v189
	v_pk_add_f32 v[152:153], v[152:153], v[242:243]
	v_pk_add_f32 v[154:155], v[154:155], v[188:189]
	v_cvt_pk_bf16_f32 v152, v152, v153
	v_cvt_pk_bf16_f32 v153, v154, v155
	v_lshlrev_b32_e32 v154, 16, v190
	v_and_b32_e32 v155, 0xffff0000, v190
	v_pk_add_f32 v[144:145], v[144:145], v[154:155]
	s_nop 0
	v_cvt_pk_bf16_f32 v154, v144, v145
	v_lshlrev_b32_e32 v144, 16, v191
	v_and_b32_e32 v145, 0xffff0000, v191
	v_pk_add_f32 v[144:145], v[146:147], v[144:145]
	v_and_b32_e32 v147, 0xffff0000, v152
	v_cvt_pk_bf16_f32 v155, v144, v145
	v_lshl_add_u64 v[144:145], s[12:13], 0, v[234:235]
	v_lshl_add_u64 v[144:145], v[144:145], 0, v[232:233]
	global_store_dwordx4 v[144:145], v[152:155], off
	v_lshlrev_b32_e32 v146, 16, v152
	v_mul_f32_e32 v147, v147, v147
	v_lshlrev_b32_e32 v152, 16, v153
	v_and_b32_e32 v153, 0xffff0000, v153
	v_fmac_f32_e32 v147, v146, v146
	v_mul_f32_e32 v146, v153, v153
	v_lshlrev_b32_e32 v188, 16, v154
	v_and_b32_e32 v154, 0xffff0000, v154
	v_lshlrev_b32_e32 v189, 16, v155
	v_and_b32_e32 v155, 0xffff0000, v155
	v_fmac_f32_e32 v146, v152, v152
	v_add_f32_e32 v146, v147, v146
	v_mul_f32_e32 v147, v154, v154
	v_mul_f32_e32 v152, v155, v155
	v_fmac_f32_e32 v147, v188, v188
	v_fmac_f32_e32 v152, v189, v189
	v_add_f32_e32 v147, v147, v152
	v_add_f32_e32 v152, v146, v147
	v_lshlrev_b32_e32 v146, 16, v184
	v_and_b32_e32 v147, 0xffff0000, v184
	v_pk_add_f32 v[132:133], v[132:133], v[146:147]
	v_lshlrev_b32_e32 v146, 16, v185
	v_and_b32_e32 v147, 0xffff0000, v185
	v_pk_add_f32 v[134:135], v[134:135], v[146:147]
	v_cvt_pk_bf16_f32 v132, v132, v133
	v_cvt_pk_bf16_f32 v133, v134, v135
	v_lshlrev_b32_e32 v134, 16, v186
	v_and_b32_e32 v135, 0xffff0000, v186
	v_pk_add_f32 v[128:129], v[128:129], v[134:135]
	s_nop 0
	v_cvt_pk_bf16_f32 v134, v128, v129
	v_lshlrev_b32_e32 v128, 16, v187
	v_and_b32_e32 v129, 0xffff0000, v187
	v_pk_add_f32 v[128:129], v[130:131], v[128:129]
	v_and_b32_e32 v131, 0xffff0000, v133
	v_cvt_pk_bf16_f32 v135, v128, v129
	v_and_b32_e32 v129, 0xffff0000, v132
	v_lshlrev_b32_e32 v128, 16, v132
	v_mul_f32_e32 v129, v129, v129
	v_lshlrev_b32_e32 v130, 16, v133
	v_fmac_f32_e32 v129, v128, v128
	v_mul_f32_e32 v128, v131, v131
	global_store_dwordx4 v[144:145], v[132:135], off offset:256
	v_fmac_f32_e32 v128, v130, v130
	v_add_f32_e32 v128, v129, v128
	v_lshlrev_b32_e32 v132, 16, v134
	v_and_b32_e32 v133, 0xffff0000, v134
	v_lshlrev_b32_e32 v134, 16, v135
	v_and_b32_e32 v135, 0xffff0000, v135
	v_mul_f32_e32 v129, v133, v133
	v_mul_f32_e32 v130, v135, v135
	v_fmac_f32_e32 v129, v132, v132
	v_fmac_f32_e32 v130, v134, v134
	v_add_f32_e32 v129, v129, v130
	v_add_f32_e32 v128, v128, v129
	v_add_f32_e32 v128, v152, v128
	v_mov_b32_e32 v129, v128
	s_nop 1
	v_permlane16_swap_b32 v129, v128
	s_waitcnt lgkmcnt(0)
	v_add_f32_e32 v128, v128, v129
	v_mov_b32_e32 v129, v128
	s_nop 1
	v_permlane32_swap_b32 v129, v128
	s_and_saveexec_b64 s[24:25], s[4:5]
	s_cbranch_execz .LBB0_1009
	s_waitcnt lgkmcnt(0)
	v_add_f32_e32 v130, v128, v129
	v_lshlrev_b64 v[128:129], 6, v[214:215]
	v_lshl_add_u64 v[128:129], s[14:15], 0, v[128:129]
	v_lshl_add_u64 v[128:129], s[22:23], 2, v[128:129]
	s_lshl_b32 s68, s46, 2
	v_lshl_add_u64 v[128:129], v[128:129], 0, s[68:69]
	global_store_dword v[128:129], v130, off
.LBB0_1009:
	s_or_b64 exec, exec, s[24:25]
	v_lshlrev_b32_e32 v128, 16, v180
	s_waitcnt lgkmcnt(0)
	v_and_b32_e32 v129, 0xffff0000, v180
	v_pk_add_f32 v[120:121], v[120:121], v[128:129]
	v_lshlrev_b32_e32 v128, 16, v181
	v_and_b32_e32 v129, 0xffff0000, v181
	v_pk_add_f32 v[122:123], v[122:123], v[128:129]
	v_cvt_pk_bf16_f32 v120, v120, v121
	v_cvt_pk_bf16_f32 v121, v122, v123
	v_lshlrev_b32_e32 v122, 16, v182
	v_and_b32_e32 v123, 0xffff0000, v182
	v_pk_add_f32 v[116:117], v[116:117], v[122:123]
	s_nop 0
	v_cvt_pk_bf16_f32 v122, v116, v117
	v_lshlrev_b32_e32 v116, 16, v183
	v_and_b32_e32 v117, 0xffff0000, v183
	v_pk_add_f32 v[116:117], v[118:119], v[116:117]
	v_and_b32_e32 v119, 0xffff0000, v121
	v_cvt_pk_bf16_f32 v123, v116, v117
	v_and_b32_e32 v117, 0xffff0000, v120
	v_lshlrev_b32_e32 v116, 16, v120
	v_mul_f32_e32 v117, v117, v117
	v_lshlrev_b32_e32 v118, 16, v121
	v_fmac_f32_e32 v117, v116, v116
	v_mul_f32_e32 v116, v119, v119
	v_and_b32_e32 v129, 0xffff0000, v122
	v_and_b32_e32 v131, 0xffff0000, v123
	v_fmac_f32_e32 v116, v118, v118
	v_lshlrev_b32_e32 v128, 16, v122
	v_lshlrev_b32_e32 v130, 16, v123
	v_add_f32_e32 v116, v117, v116
	v_mul_f32_e32 v117, v129, v129
	v_mul_f32_e32 v118, v131, v131
	v_fmac_f32_e32 v117, v128, v128
	v_fmac_f32_e32 v118, v130, v130
	v_add_f32_e32 v117, v117, v118
	v_add_f32_e32 v118, v116, v117
	v_lshlrev_b32_e32 v116, 16, v176
	v_and_b32_e32 v117, 0xffff0000, v176
	v_pk_add_f32 v[108:109], v[108:109], v[116:117]
	v_lshlrev_b32_e32 v116, 16, v177
	v_and_b32_e32 v117, 0xffff0000, v177
	v_pk_add_f32 v[110:111], v[110:111], v[116:117]
	v_cvt_pk_bf16_f32 v108, v108, v109
	v_cvt_pk_bf16_f32 v109, v110, v111
	v_lshlrev_b32_e32 v110, 16, v178
	v_and_b32_e32 v111, 0xffff0000, v178
	v_pk_add_f32 v[104:105], v[104:105], v[110:111]
	s_nop 0
	v_cvt_pk_bf16_f32 v110, v104, v105
	v_lshlrev_b32_e32 v104, 16, v179
	v_and_b32_e32 v105, 0xffff0000, v179
	v_pk_add_f32 v[104:105], v[106:107], v[104:105]
	v_and_b32_e32 v107, 0xffff0000, v109
	v_cvt_pk_bf16_f32 v111, v104, v105
	v_and_b32_e32 v105, 0xffff0000, v108
	v_lshlrev_b32_e32 v104, 16, v108
	v_mul_f32_e32 v105, v105, v105
	v_lshlrev_b32_e32 v106, 16, v109
	v_fmac_f32_e32 v105, v104, v104
	v_mul_f32_e32 v104, v107, v107
	v_and_b32_e32 v117, 0xffff0000, v110
	v_and_b32_e32 v128, 0xffff0000, v111
	v_fmac_f32_e32 v104, v106, v106
	v_lshlrev_b32_e32 v116, 16, v110
	v_lshlrev_b32_e32 v119, 16, v111
	v_add_f32_e32 v104, v105, v104
	v_mul_f32_e32 v105, v117, v117
	v_mul_f32_e32 v106, v128, v128
	v_fmac_f32_e32 v105, v116, v116
	v_fmac_f32_e32 v106, v119, v119
	v_add_f32_e32 v105, v105, v106
	v_add_f32_e32 v104, v104, v105
	v_add_f32_e32 v104, v118, v104
	v_mov_b32_e32 v105, v104
	s_nop 1
	v_permlane16_swap_b32 v105, v104
	v_lshl_add_u64 v[106:107], s[12:13], 0, v[230:231]
	v_lshl_add_u64 v[106:107], v[212:213], 1, v[106:107]
	global_store_dwordx4 v[106:107], v[120:123], off
	global_store_dwordx4 v[106:107], v[108:111], off offset:256
	s_waitcnt lgkmcnt(0)
	v_add_f32_e32 v104, v104, v105
	v_mov_b32_e32 v105, v104
	s_nop 1
	v_permlane32_swap_b32 v105, v104
	s_and_saveexec_b64 s[24:25], s[4:5]
	s_cbranch_execz .LBB0_1011
	s_waitcnt lgkmcnt(0)
	v_add_f32_e32 v106, v104, v105
	v_lshlrev_b64 v[104:105], 6, v[228:229]
	v_lshl_add_u64 v[104:105], s[14:15], 0, v[104:105]
	v_lshl_add_u64 v[104:105], s[22:23], 2, v[104:105]
	s_lshl_b32 s68, s46, 2
	v_lshl_add_u64 v[104:105], v[104:105], 0, s[68:69]
	global_store_dword v[104:105], v106, off
.LBB0_1011:
	s_or_b64 exec, exec, s[24:25]
	v_lshlrev_b32_e32 v104, 16, v172
	s_waitcnt lgkmcnt(0)
	v_and_b32_e32 v105, 0xffff0000, v172
	v_pk_add_f32 v[96:97], v[96:97], v[104:105]
	v_lshlrev_b32_e32 v104, 16, v173
	v_and_b32_e32 v105, 0xffff0000, v173
	v_pk_add_f32 v[98:99], v[98:99], v[104:105]
	v_cvt_pk_bf16_f32 v96, v96, v97
	v_cvt_pk_bf16_f32 v97, v98, v99
	v_lshlrev_b32_e32 v98, 16, v174
	v_and_b32_e32 v99, 0xffff0000, v174
	v_pk_add_f32 v[92:93], v[92:93], v[98:99]
	s_nop 0
	v_cvt_pk_bf16_f32 v98, v92, v93
	v_lshlrev_b32_e32 v92, 16, v175
	v_and_b32_e32 v93, 0xffff0000, v175
	v_pk_add_f32 v[92:93], v[94:95], v[92:93]
	v_and_b32_e32 v95, 0xffff0000, v97
	v_cvt_pk_bf16_f32 v99, v92, v93
	v_and_b32_e32 v93, 0xffff0000, v96
	v_lshlrev_b32_e32 v92, 16, v96
	v_mul_f32_e32 v93, v93, v93
	v_lshlrev_b32_e32 v94, 16, v97
	v_fmac_f32_e32 v93, v92, v92
	v_mul_f32_e32 v92, v95, v95
	v_and_b32_e32 v105, 0xffff0000, v98
	v_and_b32_e32 v107, 0xffff0000, v99
	v_fmac_f32_e32 v92, v94, v94
	v_lshlrev_b32_e32 v104, 16, v98
	v_lshlrev_b32_e32 v106, 16, v99
	v_add_f32_e32 v92, v93, v92
	v_mul_f32_e32 v93, v105, v105
	v_mul_f32_e32 v94, v107, v107
	v_fmac_f32_e32 v93, v104, v104
	v_fmac_f32_e32 v94, v106, v106
	v_add_f32_e32 v93, v93, v94
	v_add_f32_e32 v94, v92, v93
	v_lshlrev_b32_e32 v92, 16, v168
	v_and_b32_e32 v93, 0xffff0000, v168
	v_pk_add_f32 v[84:85], v[84:85], v[92:93]
	v_lshlrev_b32_e32 v92, 16, v169
	v_and_b32_e32 v93, 0xffff0000, v169
	v_pk_add_f32 v[86:87], v[86:87], v[92:93]
	v_cvt_pk_bf16_f32 v84, v84, v85
	v_cvt_pk_bf16_f32 v85, v86, v87
	v_lshlrev_b32_e32 v86, 16, v170
	v_and_b32_e32 v87, 0xffff0000, v170
	v_pk_add_f32 v[80:81], v[80:81], v[86:87]
	s_nop 0
	v_cvt_pk_bf16_f32 v86, v80, v81
	v_lshlrev_b32_e32 v80, 16, v171
	v_and_b32_e32 v81, 0xffff0000, v171
	v_pk_add_f32 v[80:81], v[82:83], v[80:81]
	v_and_b32_e32 v83, 0xffff0000, v85
	v_cvt_pk_bf16_f32 v87, v80, v81
	v_and_b32_e32 v81, 0xffff0000, v84
	v_lshlrev_b32_e32 v80, 16, v84
	v_mul_f32_e32 v81, v81, v81
	v_lshlrev_b32_e32 v82, 16, v85
	v_fmac_f32_e32 v81, v80, v80
	v_mul_f32_e32 v80, v83, v83
	v_and_b32_e32 v93, 0xffff0000, v86
	v_and_b32_e32 v104, 0xffff0000, v87
	v_fmac_f32_e32 v80, v82, v82
	v_lshlrev_b32_e32 v92, 16, v86
	v_lshlrev_b32_e32 v95, 16, v87
	v_add_f32_e32 v80, v81, v80
	v_mul_f32_e32 v81, v93, v93
	v_mul_f32_e32 v82, v104, v104
	v_fmac_f32_e32 v81, v92, v92
	v_fmac_f32_e32 v82, v95, v95
	v_add_f32_e32 v81, v81, v82
	v_add_f32_e32 v80, v80, v81
	v_add_f32_e32 v80, v94, v80
	v_mov_b32_e32 v81, v80
	s_nop 1
	v_permlane16_swap_b32 v81, v80
	v_lshl_add_u64 v[82:83], s[12:13], 0, v[226:227]
	v_lshl_add_u64 v[82:83], v[212:213], 1, v[82:83]
	global_store_dwordx4 v[82:83], v[96:99], off
	global_store_dwordx4 v[82:83], v[84:87], off offset:256
	s_waitcnt lgkmcnt(0)
	v_add_f32_e32 v80, v80, v81
	v_mov_b32_e32 v81, v80
	s_nop 1
	v_permlane32_swap_b32 v81, v80
	s_and_saveexec_b64 s[24:25], s[4:5]
	s_cbranch_execz .LBB0_1013
	s_waitcnt lgkmcnt(0)
	v_add_f32_e32 v82, v80, v81
	v_lshlrev_b64 v[80:81], 6, v[224:225]
	v_lshl_add_u64 v[80:81], s[14:15], 0, v[80:81]
	v_lshl_add_u64 v[80:81], s[22:23], 2, v[80:81]
	s_lshl_b32 s68, s46, 2
	v_lshl_add_u64 v[80:81], v[80:81], 0, s[68:69]
	global_store_dword v[80:81], v82, off
.LBB0_1013:
	s_or_b64 exec, exec, s[24:25]
	v_lshlrev_b32_e32 v80, 16, v164
	s_waitcnt lgkmcnt(0)
	v_and_b32_e32 v81, 0xffff0000, v164
	v_pk_add_f32 v[76:77], v[76:77], v[80:81]
	v_lshlrev_b32_e32 v80, 16, v165
	v_and_b32_e32 v81, 0xffff0000, v165
	v_pk_add_f32 v[78:79], v[78:79], v[80:81]
	v_cvt_pk_bf16_f32 v76, v76, v77
	v_cvt_pk_bf16_f32 v77, v78, v79
	v_lshlrev_b32_e32 v78, 16, v166
	v_and_b32_e32 v79, 0xffff0000, v166
	v_pk_add_f32 v[72:73], v[72:73], v[78:79]
	s_nop 0
	v_cvt_pk_bf16_f32 v78, v72, v73
	v_lshlrev_b32_e32 v72, 16, v167
	v_and_b32_e32 v73, 0xffff0000, v167
	v_pk_add_f32 v[72:73], v[74:75], v[72:73]
	v_and_b32_e32 v75, 0xffff0000, v77
	v_cvt_pk_bf16_f32 v79, v72, v73
	v_and_b32_e32 v73, 0xffff0000, v76
	v_lshlrev_b32_e32 v72, 16, v76
	v_mul_f32_e32 v73, v73, v73
	v_lshlrev_b32_e32 v74, 16, v77
	v_fmac_f32_e32 v73, v72, v72
	v_mul_f32_e32 v72, v75, v75
	v_and_b32_e32 v81, 0xffff0000, v78
	v_and_b32_e32 v83, 0xffff0000, v79
	v_fmac_f32_e32 v72, v74, v74
	v_lshlrev_b32_e32 v80, 16, v78
	v_lshlrev_b32_e32 v82, 16, v79
	v_add_f32_e32 v72, v73, v72
	v_mul_f32_e32 v73, v81, v81
	v_mul_f32_e32 v74, v83, v83
	v_fmac_f32_e32 v73, v80, v80
	v_fmac_f32_e32 v74, v82, v82
	v_add_f32_e32 v73, v73, v74
	v_add_f32_e32 v74, v72, v73
	v_lshlrev_b32_e32 v72, 16, v160
	v_and_b32_e32 v73, 0xffff0000, v160
	v_pk_add_f32 v[68:69], v[68:69], v[72:73]
	v_lshlrev_b32_e32 v72, 16, v161
	v_and_b32_e32 v73, 0xffff0000, v161
	v_pk_add_f32 v[70:71], v[70:71], v[72:73]
	v_cvt_pk_bf16_f32 v68, v68, v69
	v_cvt_pk_bf16_f32 v69, v70, v71
	v_lshlrev_b32_e32 v70, 16, v162
	v_and_b32_e32 v71, 0xffff0000, v162
	v_pk_add_f32 v[64:65], v[64:65], v[70:71]
	s_nop 0
	v_cvt_pk_bf16_f32 v70, v64, v65
	v_lshlrev_b32_e32 v64, 16, v163
	v_and_b32_e32 v65, 0xffff0000, v163
	v_pk_add_f32 v[64:65], v[66:67], v[64:65]
	v_and_b32_e32 v67, 0xffff0000, v69
	v_cvt_pk_bf16_f32 v71, v64, v65
	v_and_b32_e32 v65, 0xffff0000, v68
	v_lshlrev_b32_e32 v64, 16, v68
	v_mul_f32_e32 v65, v65, v65
	v_lshlrev_b32_e32 v66, 16, v69
	v_fmac_f32_e32 v65, v64, v64
	v_mul_f32_e32 v64, v67, v67
	v_and_b32_e32 v73, 0xffff0000, v70
	v_and_b32_e32 v80, 0xffff0000, v71
	v_fmac_f32_e32 v64, v66, v66
	v_lshlrev_b32_e32 v72, 16, v70
	v_lshlrev_b32_e32 v75, 16, v71
	v_add_f32_e32 v64, v65, v64
	v_mul_f32_e32 v65, v73, v73
	v_mul_f32_e32 v66, v80, v80
	v_fmac_f32_e32 v65, v72, v72
	v_fmac_f32_e32 v66, v75, v75
	v_add_f32_e32 v65, v65, v66
	v_add_f32_e32 v64, v64, v65
	v_add_f32_e32 v64, v74, v64
	v_mov_b32_e32 v65, v64
	s_nop 1
	v_permlane16_swap_b32 v65, v64
	v_lshl_add_u64 v[66:67], s[12:13], 0, v[222:223]
	v_lshl_add_u64 v[66:67], v[212:213], 1, v[66:67]
	global_store_dwordx4 v[66:67], v[76:79], off
	global_store_dwordx4 v[66:67], v[68:71], off offset:256
	s_waitcnt lgkmcnt(0)
	v_add_f32_e32 v64, v64, v65
	v_mov_b32_e32 v65, v64
	s_nop 1
	v_permlane32_swap_b32 v65, v64
	s_and_saveexec_b64 s[24:25], s[4:5]
	s_cbranch_execz .LBB0_1015
	s_waitcnt lgkmcnt(0)
	v_add_f32_e32 v66, v64, v65
	v_lshlrev_b64 v[64:65], 6, v[220:221]
	v_lshl_add_u64 v[64:65], s[14:15], 0, v[64:65]
	v_lshl_add_u64 v[64:65], s[22:23], 2, v[64:65]
	s_lshl_b32 s68, s46, 2
	v_lshl_add_u64 v[64:65], v[64:65], 0, s[68:69]
	global_store_dword v[64:65], v66, off
.LBB0_1015:
	s_or_b64 exec, exec, s[24:25]
	v_lshlrev_b32_e32 v64, 16, v156
	s_waitcnt lgkmcnt(0)
	v_and_b32_e32 v65, 0xffff0000, v156
	v_pk_add_f32 v[60:61], v[60:61], v[64:65]
	v_lshlrev_b32_e32 v64, 16, v157
	v_and_b32_e32 v65, 0xffff0000, v157
	v_pk_add_f32 v[62:63], v[62:63], v[64:65]
	v_cvt_pk_bf16_f32 v60, v60, v61
	v_cvt_pk_bf16_f32 v61, v62, v63
	v_lshlrev_b32_e32 v62, 16, v158
	v_and_b32_e32 v63, 0xffff0000, v158
	v_pk_add_f32 v[56:57], v[56:57], v[62:63]
	s_nop 0
	v_cvt_pk_bf16_f32 v62, v56, v57
	v_lshlrev_b32_e32 v56, 16, v159
	v_and_b32_e32 v57, 0xffff0000, v159
	v_pk_add_f32 v[56:57], v[58:59], v[56:57]
	v_and_b32_e32 v59, 0xffff0000, v61
	v_cvt_pk_bf16_f32 v63, v56, v57
	v_and_b32_e32 v57, 0xffff0000, v60
	v_lshlrev_b32_e32 v56, 16, v60
	v_mul_f32_e32 v57, v57, v57
	v_lshlrev_b32_e32 v58, 16, v61
	v_fmac_f32_e32 v57, v56, v56
	v_mul_f32_e32 v56, v59, v59
	v_and_b32_e32 v65, 0xffff0000, v62
	v_and_b32_e32 v67, 0xffff0000, v63
	v_fmac_f32_e32 v56, v58, v58
	v_lshlrev_b32_e32 v64, 16, v62
	v_lshlrev_b32_e32 v66, 16, v63
	v_add_f32_e32 v56, v57, v56
	v_mul_f32_e32 v57, v65, v65
	v_mul_f32_e32 v58, v67, v67
	v_fmac_f32_e32 v57, v64, v64
	v_fmac_f32_e32 v58, v66, v66
	v_add_f32_e32 v57, v57, v58
	v_add_f32_e32 v58, v56, v57
	v_lshlrev_b32_e32 v56, 16, v148
	v_and_b32_e32 v57, 0xffff0000, v148
	v_pk_add_f32 v[52:53], v[52:53], v[56:57]
	v_lshlrev_b32_e32 v56, 16, v149
	v_and_b32_e32 v57, 0xffff0000, v149
	v_pk_add_f32 v[54:55], v[54:55], v[56:57]
	v_cvt_pk_bf16_f32 v52, v52, v53
	v_cvt_pk_bf16_f32 v53, v54, v55
	v_lshlrev_b32_e32 v54, 16, v150
	v_and_b32_e32 v55, 0xffff0000, v150
	v_pk_add_f32 v[48:49], v[48:49], v[54:55]
	s_nop 0
	v_cvt_pk_bf16_f32 v54, v48, v49
	v_lshlrev_b32_e32 v48, 16, v151
	v_and_b32_e32 v49, 0xffff0000, v151
	v_pk_add_f32 v[48:49], v[50:51], v[48:49]
	v_and_b32_e32 v51, 0xffff0000, v53
	v_cvt_pk_bf16_f32 v55, v48, v49
	v_and_b32_e32 v49, 0xffff0000, v52
	v_lshlrev_b32_e32 v48, 16, v52
	v_mul_f32_e32 v49, v49, v49
	v_lshlrev_b32_e32 v50, 16, v53
	v_fmac_f32_e32 v49, v48, v48
	v_mul_f32_e32 v48, v51, v51
	v_and_b32_e32 v57, 0xffff0000, v54
	v_and_b32_e32 v64, 0xffff0000, v55
	v_fmac_f32_e32 v48, v50, v50
	v_lshlrev_b32_e32 v56, 16, v54
	v_lshlrev_b32_e32 v59, 16, v55
	v_add_f32_e32 v48, v49, v48
	v_mul_f32_e32 v49, v57, v57
	v_mul_f32_e32 v50, v64, v64
	v_fmac_f32_e32 v49, v56, v56
	v_fmac_f32_e32 v50, v59, v59
	v_add_f32_e32 v49, v49, v50
	v_add_f32_e32 v48, v48, v49
	v_add_f32_e32 v48, v58, v48
	v_mov_b32_e32 v49, v48
	s_nop 1
	v_permlane16_swap_b32 v49, v48
	v_lshl_add_u64 v[50:51], s[12:13], 0, v[218:219]
	v_lshl_add_u64 v[50:51], v[212:213], 1, v[50:51]
	global_store_dwordx4 v[50:51], v[60:63], off
	global_store_dwordx4 v[50:51], v[52:55], off offset:256
	s_waitcnt lgkmcnt(0)
	v_add_f32_e32 v48, v48, v49
	v_mov_b32_e32 v49, v48
	s_nop 1
	v_permlane32_swap_b32 v49, v48
	s_and_saveexec_b64 s[24:25], s[4:5]
	s_cbranch_execz .LBB0_1017
	s_waitcnt lgkmcnt(0)
	v_add_f32_e32 v50, v48, v49
	v_lshlrev_b64 v[48:49], 6, v[216:217]
	v_lshl_add_u64 v[48:49], s[14:15], 0, v[48:49]
	v_lshl_add_u64 v[48:49], s[22:23], 2, v[48:49]
	s_lshl_b32 s68, s46, 2
	v_lshl_add_u64 v[48:49], v[48:49], 0, s[68:69]
	global_store_dword v[48:49], v50, off
.LBB0_1017:
	s_or_b64 exec, exec, s[24:25]
	v_lshlrev_b32_e32 v48, 16, v140
	s_waitcnt lgkmcnt(0)
	v_and_b32_e32 v49, 0xffff0000, v140
	v_pk_add_f32 v[44:45], v[44:45], v[48:49]
	v_lshlrev_b32_e32 v48, 16, v141
	v_and_b32_e32 v49, 0xffff0000, v141
	v_pk_add_f32 v[46:47], v[46:47], v[48:49]
	v_cvt_pk_bf16_f32 v44, v44, v45
	v_cvt_pk_bf16_f32 v45, v46, v47
	v_lshlrev_b32_e32 v46, 16, v142
	v_and_b32_e32 v47, 0xffff0000, v142
	v_pk_add_f32 v[40:41], v[40:41], v[46:47]
	s_nop 0
	v_cvt_pk_bf16_f32 v46, v40, v41
	v_lshlrev_b32_e32 v40, 16, v143
	v_and_b32_e32 v41, 0xffff0000, v143
	v_pk_add_f32 v[40:41], v[42:43], v[40:41]
	v_and_b32_e32 v43, 0xffff0000, v45
	v_cvt_pk_bf16_f32 v47, v40, v41
	v_and_b32_e32 v41, 0xffff0000, v44
	v_lshlrev_b32_e32 v40, 16, v44
	v_mul_f32_e32 v41, v41, v41
	v_lshlrev_b32_e32 v42, 16, v45
	v_fmac_f32_e32 v41, v40, v40
	v_mul_f32_e32 v40, v43, v43
	v_and_b32_e32 v49, 0xffff0000, v46
	v_and_b32_e32 v51, 0xffff0000, v47
	v_fmac_f32_e32 v40, v42, v42
	v_lshlrev_b32_e32 v48, 16, v46
	v_lshlrev_b32_e32 v50, 16, v47
	v_add_f32_e32 v40, v41, v40
	v_mul_f32_e32 v41, v49, v49
	v_mul_f32_e32 v42, v51, v51
	v_fmac_f32_e32 v41, v48, v48
	v_fmac_f32_e32 v42, v50, v50
	v_add_f32_e32 v41, v41, v42
	v_add_f32_e32 v42, v40, v41
	v_lshlrev_b32_e32 v40, 16, v136
	v_and_b32_e32 v41, 0xffff0000, v136
	v_pk_add_f32 v[36:37], v[36:37], v[40:41]
	v_lshlrev_b32_e32 v40, 16, v137
	v_and_b32_e32 v41, 0xffff0000, v137
	v_pk_add_f32 v[38:39], v[38:39], v[40:41]
	v_cvt_pk_bf16_f32 v36, v36, v37
	v_cvt_pk_bf16_f32 v37, v38, v39
	v_lshlrev_b32_e32 v38, 16, v138
	v_and_b32_e32 v39, 0xffff0000, v138
	v_pk_add_f32 v[32:33], v[32:33], v[38:39]
	s_nop 0
	v_cvt_pk_bf16_f32 v38, v32, v33
	v_lshlrev_b32_e32 v32, 16, v139
	v_and_b32_e32 v33, 0xffff0000, v139
	v_pk_add_f32 v[32:33], v[34:35], v[32:33]
	v_and_b32_e32 v35, 0xffff0000, v37
	v_cvt_pk_bf16_f32 v39, v32, v33
	v_and_b32_e32 v33, 0xffff0000, v36
	v_lshlrev_b32_e32 v32, 16, v36
	v_mul_f32_e32 v33, v33, v33
	v_lshlrev_b32_e32 v34, 16, v37
	v_fmac_f32_e32 v33, v32, v32
	v_mul_f32_e32 v32, v35, v35
	v_and_b32_e32 v41, 0xffff0000, v38
	v_and_b32_e32 v48, 0xffff0000, v39
	v_fmac_f32_e32 v32, v34, v34
	v_lshlrev_b32_e32 v40, 16, v38
	v_lshlrev_b32_e32 v43, 16, v39
	v_add_f32_e32 v32, v33, v32
	v_mul_f32_e32 v33, v41, v41
	v_mul_f32_e32 v34, v48, v48
	v_fmac_f32_e32 v33, v40, v40
	v_fmac_f32_e32 v34, v43, v43
	v_add_f32_e32 v33, v33, v34
	v_add_f32_e32 v32, v32, v33
	v_add_f32_e32 v34, v42, v32
	v_mov_b32_e32 v35, v34
	s_nop 1
	v_permlane16_swap_b32 v35, v34
	v_add_u32_e32 v32, 0x90, v214
	v_ashrrev_i32_e32 v33, 31, v32
	v_lshlrev_b64 v[40:41], 11, v[32:33]
	v_lshl_add_u64 v[40:41], s[12:13], 0, v[40:41]
	s_waitcnt lgkmcnt(0)
	v_add_f32_e32 v34, v34, v35
	v_mov_b32_e32 v35, v34
	s_nop 1
	v_permlane32_swap_b32 v35, v34
	v_lshl_add_u64 v[40:41], v[212:213], 1, v[40:41]
	global_store_dwordx4 v[40:41], v[44:47], off
	global_store_dwordx4 v[40:41], v[36:39], off offset:256
	s_and_saveexec_b64 s[24:25], s[4:5]
	s_cbranch_execz .LBB0_1019
	v_lshlrev_b64 v[32:33], 6, v[32:33]
	v_lshl_add_u64 v[32:33], s[14:15], 0, v[32:33]
	v_lshl_add_u64 v[32:33], s[22:23], 2, v[32:33]
	s_lshl_b32 s68, s46, 2
	s_waitcnt lgkmcnt(0)
	v_add_f32_e32 v34, v34, v35
	v_lshl_add_u64 v[32:33], v[32:33], 0, s[68:69]
	global_store_dword v[32:33], v34, off
.LBB0_1019:
	s_or_b64 exec, exec, s[24:25]
	v_lshlrev_b32_e32 v32, 16, v124
	v_and_b32_e32 v33, 0xffff0000, v124
	v_pk_add_f32 v[28:29], v[28:29], v[32:33]
	v_lshlrev_b32_e32 v32, 16, v125
	v_and_b32_e32 v33, 0xffff0000, v125
	v_pk_add_f32 v[30:31], v[30:31], v[32:33]
	v_cvt_pk_bf16_f32 v28, v28, v29
	v_cvt_pk_bf16_f32 v29, v30, v31
	v_lshlrev_b32_e32 v30, 16, v126
	v_and_b32_e32 v31, 0xffff0000, v126
	v_pk_add_f32 v[24:25], v[24:25], v[30:31]
	s_nop 0
	v_cvt_pk_bf16_f32 v30, v24, v25
	v_lshlrev_b32_e32 v24, 16, v127
	v_and_b32_e32 v25, 0xffff0000, v127
	v_pk_add_f32 v[24:25], v[26:27], v[24:25]
	v_and_b32_e32 v27, 0xffff0000, v29
	v_cvt_pk_bf16_f32 v31, v24, v25
	v_and_b32_e32 v25, 0xffff0000, v28
	v_lshlrev_b32_e32 v24, 16, v28
	v_mul_f32_e32 v25, v25, v25
	v_lshlrev_b32_e32 v26, 16, v29
	v_fmac_f32_e32 v25, v24, v24
	v_mul_f32_e32 v24, v27, v27
	v_and_b32_e32 v33, 0xffff0000, v30
	s_waitcnt lgkmcnt(0)
	v_and_b32_e32 v35, 0xffff0000, v31
	v_fmac_f32_e32 v24, v26, v26
	v_lshlrev_b32_e32 v32, 16, v30
	v_lshlrev_b32_e32 v34, 16, v31
	v_add_f32_e32 v24, v25, v24
	v_mul_f32_e32 v25, v33, v33
	v_mul_f32_e32 v26, v35, v35
	v_fmac_f32_e32 v25, v32, v32
	v_fmac_f32_e32 v26, v34, v34
	v_add_f32_e32 v25, v25, v26
	v_add_f32_e32 v26, v24, v25
	v_lshlrev_b32_e32 v24, 16, v112
	v_and_b32_e32 v25, 0xffff0000, v112
	v_pk_add_f32 v[20:21], v[20:21], v[24:25]
	v_lshlrev_b32_e32 v24, 16, v113
	v_and_b32_e32 v25, 0xffff0000, v113
	v_pk_add_f32 v[22:23], v[22:23], v[24:25]
	v_cvt_pk_bf16_f32 v20, v20, v21
	v_cvt_pk_bf16_f32 v21, v22, v23
	v_lshlrev_b32_e32 v22, 16, v114
	v_and_b32_e32 v23, 0xffff0000, v114
	v_pk_add_f32 v[16:17], v[16:17], v[22:23]
	s_nop 0
	v_cvt_pk_bf16_f32 v22, v16, v17
	v_lshlrev_b32_e32 v16, 16, v115
	v_and_b32_e32 v17, 0xffff0000, v115
	v_pk_add_f32 v[16:17], v[18:19], v[16:17]
	v_and_b32_e32 v19, 0xffff0000, v21
	v_cvt_pk_bf16_f32 v23, v16, v17
	v_and_b32_e32 v17, 0xffff0000, v20
	v_lshlrev_b32_e32 v16, 16, v20
	v_mul_f32_e32 v17, v17, v17
	v_lshlrev_b32_e32 v18, 16, v21
	v_fmac_f32_e32 v17, v16, v16
	v_mul_f32_e32 v16, v19, v19
	v_and_b32_e32 v25, 0xffff0000, v22
	v_and_b32_e32 v32, 0xffff0000, v23
	v_fmac_f32_e32 v16, v18, v18
	v_lshlrev_b32_e32 v24, 16, v22
	v_lshlrev_b32_e32 v27, 16, v23
	v_add_f32_e32 v16, v17, v16
	v_mul_f32_e32 v17, v25, v25
	v_mul_f32_e32 v18, v32, v32
	v_fmac_f32_e32 v17, v24, v24
	v_fmac_f32_e32 v18, v27, v27
	v_add_f32_e32 v17, v17, v18
	v_add_f32_e32 v16, v16, v17
	v_add_f32_e32 v18, v26, v16
	v_mov_b32_e32 v19, v18
	s_nop 1
	v_permlane16_swap_b32 v19, v18
	v_add_u32_e32 v16, 0xa0, v214
	v_ashrrev_i32_e32 v17, 31, v16
	v_lshlrev_b64 v[24:25], 11, v[16:17]
	v_lshl_add_u64 v[24:25], s[12:13], 0, v[24:25]
	s_waitcnt lgkmcnt(0)
	v_add_f32_e32 v18, v18, v19
	v_mov_b32_e32 v19, v18
	s_nop 1
	v_permlane32_swap_b32 v19, v18
	v_lshl_add_u64 v[24:25], v[212:213], 1, v[24:25]
	global_store_dwordx4 v[24:25], v[28:31], off
	global_store_dwordx4 v[24:25], v[20:23], off offset:256
	s_and_saveexec_b64 s[24:25], s[4:5]
	s_cbranch_execz .LBB0_1021
	v_lshlrev_b64 v[16:17], 6, v[16:17]
	v_lshl_add_u64 v[16:17], s[14:15], 0, v[16:17]
	v_lshl_add_u64 v[16:17], s[22:23], 2, v[16:17]
	s_lshl_b32 s68, s46, 2
	s_waitcnt lgkmcnt(0)
	v_add_f32_e32 v18, v18, v19
	v_lshl_add_u64 v[16:17], v[16:17], 0, s[68:69]
	global_store_dword v[16:17], v18, off
.LBB0_1021:
	s_or_b64 exec, exec, s[24:25]
	v_lshlrev_b32_e32 v16, 16, v100
	v_and_b32_e32 v17, 0xffff0000, v100
	v_pk_add_f32 v[12:13], v[12:13], v[16:17]
	v_lshlrev_b32_e32 v16, 16, v101
	v_and_b32_e32 v17, 0xffff0000, v101
	v_pk_add_f32 v[14:15], v[14:15], v[16:17]
	v_cvt_pk_bf16_f32 v12, v12, v13
	v_cvt_pk_bf16_f32 v13, v14, v15
	v_lshlrev_b32_e32 v14, 16, v102
	v_and_b32_e32 v15, 0xffff0000, v102
	v_pk_add_f32 v[8:9], v[8:9], v[14:15]
	s_nop 0
	v_cvt_pk_bf16_f32 v14, v8, v9
	v_lshlrev_b32_e32 v8, 16, v103
	v_and_b32_e32 v9, 0xffff0000, v103
	v_pk_add_f32 v[8:9], v[10:11], v[8:9]
	v_and_b32_e32 v11, 0xffff0000, v13
	v_cvt_pk_bf16_f32 v15, v8, v9
	v_and_b32_e32 v9, 0xffff0000, v12
	v_lshlrev_b32_e32 v8, 16, v12
	v_mul_f32_e32 v9, v9, v9
	v_lshlrev_b32_e32 v10, 16, v13
	v_fmac_f32_e32 v9, v8, v8
	v_mul_f32_e32 v8, v11, v11
	v_and_b32_e32 v17, 0xffff0000, v14
	s_waitcnt lgkmcnt(0)
	v_and_b32_e32 v19, 0xffff0000, v15
	v_fmac_f32_e32 v8, v10, v10
	v_lshlrev_b32_e32 v16, 16, v14
	v_lshlrev_b32_e32 v18, 16, v15
	v_add_f32_e32 v8, v9, v8
	v_mul_f32_e32 v9, v17, v17
	v_mul_f32_e32 v10, v19, v19
	v_fmac_f32_e32 v9, v16, v16
	v_fmac_f32_e32 v10, v18, v18
	v_add_f32_e32 v9, v9, v10
	v_add_f32_e32 v10, v8, v9
	v_lshlrev_b32_e32 v8, 16, v88
	v_and_b32_e32 v9, 0xffff0000, v88
	v_pk_add_f32 v[4:5], v[4:5], v[8:9]
	v_lshlrev_b32_e32 v8, 16, v89
	v_and_b32_e32 v9, 0xffff0000, v89
	v_pk_add_f32 v[6:7], v[6:7], v[8:9]
	v_cvt_pk_bf16_f32 v4, v4, v5
	v_cvt_pk_bf16_f32 v5, v6, v7
	v_lshlrev_b32_e32 v6, 16, v90
	v_and_b32_e32 v7, 0xffff0000, v90
	v_pk_add_f32 v[0:1], v[0:1], v[6:7]
	s_nop 0
	v_cvt_pk_bf16_f32 v6, v0, v1
	v_lshlrev_b32_e32 v0, 16, v91
	v_and_b32_e32 v1, 0xffff0000, v91
	v_pk_add_f32 v[0:1], v[2:3], v[0:1]
	v_and_b32_e32 v3, 0xffff0000, v5
	v_cvt_pk_bf16_f32 v7, v0, v1
	v_and_b32_e32 v1, 0xffff0000, v4
	v_lshlrev_b32_e32 v0, 16, v4
	v_mul_f32_e32 v1, v1, v1
	v_lshlrev_b32_e32 v2, 16, v5
	v_fmac_f32_e32 v1, v0, v0
	v_mul_f32_e32 v0, v3, v3
	v_and_b32_e32 v9, 0xffff0000, v6
	v_and_b32_e32 v16, 0xffff0000, v7
	v_fmac_f32_e32 v0, v2, v2
	v_lshlrev_b32_e32 v8, 16, v6
	v_lshlrev_b32_e32 v11, 16, v7
	v_add_f32_e32 v0, v1, v0
	v_mul_f32_e32 v1, v9, v9
	v_mul_f32_e32 v2, v16, v16
	v_fmac_f32_e32 v1, v8, v8
	v_fmac_f32_e32 v2, v11, v11
	v_add_f32_e32 v1, v1, v2
	v_add_f32_e32 v0, v0, v1
	v_add_f32_e32 v2, v10, v0
	v_mov_b32_e32 v3, v2
	s_nop 1
	v_permlane16_swap_b32 v3, v2
	v_add_u32_e32 v0, 0xb0, v214
	v_ashrrev_i32_e32 v1, 31, v0
	v_lshlrev_b64 v[8:9], 11, v[0:1]
	v_lshl_add_u64 v[8:9], s[12:13], 0, v[8:9]
	s_waitcnt lgkmcnt(0)
	v_add_f32_e32 v2, v2, v3
	v_mov_b32_e32 v3, v2
	s_nop 1
	v_permlane32_swap_b32 v3, v2
	v_lshl_add_u64 v[8:9], v[212:213], 1, v[8:9]
	global_store_dwordx4 v[8:9], v[12:15], off
	global_store_dwordx4 v[8:9], v[4:7], off offset:256
	s_and_saveexec_b64 s[24:25], s[4:5]
	s_cbranch_execz .LBB0_1023
	v_lshlrev_b64 v[0:1], 6, v[0:1]
	v_lshl_add_u64 v[0:1], s[14:15], 0, v[0:1]
	v_lshl_add_u64 v[0:1], s[22:23], 2, v[0:1]
	s_lshl_b32 s68, s46, 2
	s_waitcnt lgkmcnt(0)
	v_add_f32_e32 v2, v2, v3
	v_lshl_add_u64 v[0:1], v[0:1], 0, s[68:69]
	global_store_dword v[0:1], v2, off
